# plus: all remaining kernarg pointer fetches converted from flat_load+readfirstlane to s_load
# baseline (speedup 1.0000x reference)
; #define LAS __attribute__((address_space(3)))
; #define GASP __attribute__((address_space(1)))
; __device__ __forceinline__ void pp2_phase(Frame& F, unsigned char* ws, const bf16* QRAW, const bf16* KVRAW, const bf16* ZM, const float* gqn, const float* gkn) {
;     bf16* QM = (bf16*)(ws + WS_QM); bf16* KM = (bf16*)(ws + WS_KM); bf16* VTM = (bf16*)(ws + WS_VTM);
;     const float* CS = (const float*)(ws + WS_CS);
;     const int lane = F.lane, a = lane & 15, hh = lane >> 4, a8 = lane & 7, h8 = lane >> 3;
;     const f32x4 g0q = *(const GASP f32x4*)(gqn + 4 * a), g1q = *(const GASP f32x4*)(gqn + 64 + 4 * a8), g0k = *(const GASP f32x4*)(gkn + 4 * a), g1k = *(const GASP f32x4*)(gkn + 64 + 4 * a8);
;     const bool hi = (a8 & 4) != 0;
;     LAS bf16* stage = (LAS bf16*)F.lds;
;     for (int lc = F.xr; lc < 64; lc += F.nx) {
;         const int ch = 64 * F.xid + lc;
;         const int lr0 = ch * 64, bl = lr0 >> 11, s0 = lr0 & 2047;
.LBB0_221:
	s_and_b64 vcc, exec, s[6:7]
	s_cbranch_vccz .LBB0_229
	s_load_dwordx2 s[98:99], s[0:1], 0x68
	s_load_dwordx2 s[100:101], s[0:1], 0x70
	s_cmp_gt_i32 s73, 63
	s_waitcnt vmcnt(0) lgkmcnt(0)
	s_mov_b32 s8, s98
	s_mov_b32 s6, s99
	s_mov_b32 s7, s100
	s_mov_b32 s2, s101
	s_cbranch_scc1 .LBB0_229
	v_readlane_b32 s10, v248, 16
	v_readlane_b32 s11, v248, 17
	s_and_b64 s[10:11], s[10:11], exec
	s_cselect_b32 s10, 0x180, 0
	s_add_u32 s8, s8, s10
	v_lshlrev_b32_e32 v0, 2, v198
	s_addc_u32 s9, s6, 0
	v_and_b32_e32 v16, 60, v0
	v_and_b32_e32 v18, 28, v0
	s_add_u32 s6, s7, s10
	v_lshlrev_b32_e32 v4, 2, v16
	v_lshlrev_b32_e32 v12, 2, v18
	s_addc_u32 s7, s2, 0
	global_load_dwordx4 v[0:3], v4, s[8:9]
	s_nop 0
	global_load_dwordx4 v[4:7], v4, s[6:7]
	s_nop 0
	global_load_dwordx4 v[8:11], v12, s[8:9] offset:256
	s_nop 0
	global_load_dwordx4 v[12:15], v12, s[6:7] offset:256
	s_add_u32 s18, s76, 0x300000
	s_addc_u32 s19, s77, 0
	v_and_b32_e32 v17, 4, v196
	s_add_u32 s10, s76, 0x2a400000
	v_cmp_eq_u32_e64 s[6:7], 0, v17
	v_lshrrev_b32_e32 v17, 4, v198
	s_addc_u32 s11, s77, 0
	s_movk_i32 s2, 0x60
	v_lshrrev_b32_e32 v19, 3, v198
	s_add_u32 s12, s76, 0x27400000
	v_lshlrev_b32_e32 v20, 3, v198
	v_mul_u32_u24_e32 v28, 0x60, v17
	v_lshlrev_b32_e32 v50, 7, v17
	v_mad_u32_u24 v30, v17, s2, v226
	v_lshlrev_b32_e32 v141, 5, v17
	v_lshlrev_b32_e32 v17, 3, v196
	s_addc_u32 s13, s77, 0
	v_and_b32_e32 v51, 24, v20
	v_mul_u32_u24_e32 v20, 0x60, v19
	v_lshlrev_b32_e32 v192, 1, v16
	v_and_b32_e32 v17, 56, v17
	v_lshl_add_u64 v[48:49], s[12:13], 0, v[192:193]
	v_lshlrev_b32_e32 v22, 1, v20
	v_mov_b32_e32 v23, v193
	v_lshl_add_u64 v[26:27], s[10:11], 0, v[192:193]
	v_add_u32_e32 v140, 0, v192
	v_lshlrev_b32_e32 v192, 1, v17
	v_lshl_add_u64 v[24:25], s[12:13], 0, v[22:23]
	v_lshl_add_u64 v[22:23], s[10:11], 0, v[22:23]
	v_lshl_add_u64 v[32:33], s[76:77], 0, v[192:193]
	s_mov_b64 s[10:11], 0x2d400000
	v_readlane_b32 s2, v248, 37
	v_lshl_add_u64 v[54:55], v[32:33], 0, s[10:11]
	v_lshlrev_b32_e32 v192, 1, v18
	v_readlane_b32 s10, v248, 30
	v_lshlrev_b32_e32 v19, 1, v198
	s_lshl_b32 s87, s2, 3
	s_movk_i32 s2, 0x408
	v_readlane_b32 s11, v248, 31
	v_lshl_add_u64 v[58:59], v[24:25], 0, v[192:193]
	v_lshlrev_b32_e32 v24, 1, v28
	v_mov_b32_e32 v25, v193
	v_and_b32_e32 v53, 48, v19
	v_cmp_gt_u32_e64 s[8:9], 32, v198
	v_or_b32_e32 v52, 0x200, v50
	s_lshl_b32 s86, s22, 12
	v_mad_u32_u24 v142, v17, s2, 0
	v_lshl_add_u64 v[56:57], s[10:11], 0, v[192:193]
	v_lshl_add_u64 v[60:61], v[26:27], 0, v[24:25]
	v_lshl_add_u64 v[62:63], v[22:23], 0, v[192:193]
	v_lshlrev_b32_e32 v192, 1, v20
	v_lshlrev_b32_e32 v64, 1, v18
	v_lshlrev_b32_e32 v66, 1, v16
	v_lshlrev_b32_e32 v68, 1, v28
	v_lshlrev_b32_e32 v70, 1, v30
	s_mov_b32 s88, s73

; #define LAS __attribute__((address_space(3)))
; #define GASP __attribute__((address_space(1)))
; __device__ __forceinline__ void pp1_phase(Frame& F, unsigned char* ws, const bf16* ZG, const bf16* ZM, const float* gqn, const float* gkn) {
;     float* RSQ = (float*)(ws + WS_RSQ); float* RSKV = (float*)(ws + WS_RSKV);
;     bf16* QG = (bf16*)(ws + WS_QG); bf16* KG = (bf16*)(ws + WS_KG); bf16* VTG = (bf16*)(ws + WS_VTG);
;     const float* CS = (const float*)(ws + WS_CS);
;     const int lane = F.lane, a = lane & 15;
;     const f32x4 gq4 = *(const GASP f32x4*)(gqn + 4 * a), gk4 = *(const GASP f32x4*)(gkn + 4 * a);
;     const bool hi = (a & 4) != 0;
;     LAS bf16* stage = (LAS bf16*)F.lds;
;     for (int lc = F.xr; lc < 64; lc += F.nx) {
;         const int ch = 64 * F.xid + lc;
;         const int lr0 = ch * 64, bl = lr0 >> 11, s0 = lr0 & 2047;
.LBB0_255:
	s_and_b64 vcc, exec, s[6:7]
	s_cbranch_vccz .LBB0_301
	s_load_dwordx2 s[98:99], s[0:1], 0x78
	s_load_dwordx2 s[100:101], s[0:1], 0x80
	s_cmp_gt_i32 s73, 63
	s_waitcnt vmcnt(0) lgkmcnt(0)
	s_mov_b32 s7, s98
	s_mov_b32 s4, s99
	s_mov_b32 s6, s100
	s_mov_b32 s2, s101
	s_cbranch_scc1 .LBB0_301
	v_readlane_b32 s8, v248, 16
	v_readlane_b32 s9, v248, 17
	s_and_b64 s[8:9], s[8:9], exec
	s_cselect_b32 s10, 0x100, 0
	s_add_u32 s8, s7, s10
	s_addc_u32 s9, s4, 0
	v_and_b32_e32 v8, 15, v196
	s_add_u32 s6, s6, s10
	v_lshlrev_b32_e32 v4, 4, v8
	s_addc_u32 s7, s2, 0
	global_load_dwordx4 v[0:3], v4, s[8:9]
	s_nop 0
	global_load_dwordx4 v[4:7], v4, s[6:7]
	s_add_u32 s2, s76, 0x340000
	s_addc_u32 s4, s77, 0
	v_and_b32_e32 v9, 4, v196
	v_lshlrev_b32_e32 v192, 3, v198
	s_add_u32 s16, s76, 0x360000
	v_cmp_eq_u32_e64 s[6:7], 0, v9
	v_cmp_gt_u32_e64 s[12:13], 8, v8
	v_lshl_add_u64 v[8:9], s[76:77], 0, v[192:193]
	s_mov_b64 s[18:19], 0x24400000
	s_addc_u32 s17, s77, 0
	v_lshl_add_u64 v[42:43], v[8:9], 0, s[18:19]
	s_mov_b64 s[18:19], 0x26400000
	s_add_u32 s20, s76, 0x26c00000
	v_lshl_add_u64 v[44:45], v[8:9], 0, s[18:19]
	v_lshlrev_b32_e32 v8, 3, v196
	v_add_u32_e32 v11, 0x200, v196
	s_addc_u32 s21, s77, 0
	v_readlane_b32 s14, v248, 32
	v_ashrrev_i32_e32 v98, 3, v196
	v_and_b32_e32 v8, 56, v8
	v_ashrrev_i32_e32 v99, 3, v11
	v_readlane_b32 s18, v248, 30
	s_add_u32 s44, s76, 0x300000
	v_readlane_b32 s15, v248, 33
	v_lshl_add_u32 v9, v98, 1, 0
	v_mul_u32_u24_e32 v10, 0x108, v8
	v_lshl_add_u32 v11, v99, 1, 0
	v_readlane_b32 s19, v248, 31
	s_addc_u32 s45, s77, 0
	v_cmp_gt_u32_e64 s[8:9], 32, v198
	v_cmp_lt_u32_e64 s[10:11], 31, v198
	v_and_b32_e32 v96, 24, v192
	v_lshl_add_u64 v[40:41], s[14:15], 0, v[192:193]
	v_cmp_eq_u32_e64 s[14:15], 0, v198
	v_add_u32_e32 v97, 0, v192
	s_lshl_b32 s26, s22, 12
	s_lshl_b32 s27, s83, 3
	v_lshl_add_u64 v[46:47], s[18:19], 0, v[192:193]
	v_add_u32_e32 v100, v9, v10
	v_lshlrev_b32_e32 v192, 1, v8
	v_add_u32_e32 v101, v11, v10
	s_mov_b32 s28, s73
	s_branch .LBB0_259

; __global__ void __launch_bounds__(NTHR, 2) fwd_megakernel(Args args) {
;     ...
;             if (kind == 0 || kind == 3 || kind == 11) {
;                 const bool fromx = (kind == 0 && l == 0);
;                 const void* hin = fromx ? (const void*)uni(args_.in[0]) : (const void*)(ws + WS_H);
;                 const float* gain = (kind == 0 ? uni(args_.in[4]) : kind == 3 ? uni(args_.in[7]) : uni(args_.in[20])) + l * DM;
;                 const int mi = (kind == 0) ? 0 : (kind == 3) ? 3 : 6;
;                 norm_phase(F, hin, fromx ? 0 : 1, gain, modl + mi * DM, modl + (mi + 1) * DM, U_);
.LBB0_330:
	s_andn2_b64 vcc, exec, s[10:11]
	s_cbranch_vccnz .LBB0_332
	s_load_dwordx2 s[14:15], s[0:1], 0x0
	s_waitcnt vmcnt(0) lgkmcnt(0)

; __global__ void __launch_bounds__(NTHR, 2) fwd_megakernel(Args args) {
;     ...
;             if (kind == 0 || kind == 3 || kind == 11) {
;                 const bool fromx = (kind == 0 && l == 0);
;                 const void* hin = fromx ? (const void*)uni(args_.in[0]) : (const void*)(ws + WS_H);
;                 const float* gain = (kind == 0 ? uni(args_.in[4]) : kind == 3 ? uni(args_.in[7]) : uni(args_.in[20])) + l * DM;
;                 const int mi = (kind == 0) ? 0 : (kind == 3) ? 3 : 6;
;                 norm_phase(F, hin, fromx ? 0 : 1, gain, modl + mi * DM, modl + (mi + 1) * DM, U_);
.LBB0_613:
	s_andn2_b64 vcc, exec, s[12:13]
	s_cbranch_vccnz .LBB0_615
	s_load_dwordx2 s[6:7], s[0:1], 0x0
	s_waitcnt vmcnt(0) lgkmcnt(0)
.LBB0_615:
	s_cmp_eq_u32 s5, 3
	s_cselect_b64 s[12:13], -1, 0
	s_cmp_lg_u32 s5, 3
	s_cselect_b64 s[28:29], -1, 0
	s_mov_b64 s[18:19], -1
	s_and_b64 vcc, exec, s[14:15]
	s_cbranch_vccz .LBB0_622
	s_and_b64 vcc, exec, s[28:29]
	s_cbranch_vccz .LBB0_618
	s_load_dwordx2 s[14:15], s[0:1], 0xa0
	s_mov_b64 s[18:19], 0
	s_waitcnt vmcnt(0) lgkmcnt(0)
.LBB0_618:
	s_andn2_b64 vcc, exec, s[18:19]
	s_cbranch_vccnz .LBB0_620
	s_load_dwordx2 s[14:15], s[0:1], 0x38
	s_waitcnt vmcnt(0) lgkmcnt(0)

; __device__ __forceinline__ void norm_phase(Frame& F, const void* h, int h_bf, const float* gain, const float* sh, const float* sc, bf16* U) {
;     const int lw = F.xr * NWAVES + F.wave, NLW = F.nx * NWAVES;
;     for (int lb = lw; lb < 256; lb += NLW) {
; __global__ void __launch_bounds__(NTHR, 2) fwd_megakernel(Args args) {
;     ...
;                 const float* gain = (kind == 0 ? uni(args_.in[4]) : kind == 3 ? uni(args_.in[7]) : uni(args_.in[20])) + l * DM;
;                 const int mi = (kind == 0) ? 0 : (kind == 3) ? 3 : 6;
;                 norm_phase(F, hin, fromx ? 0 : 1, gain, modl + mi * DM, modl + (mi + 1) * DM, U_);
.LBB0_623:
	s_load_dwordx2 s[14:15], s[0:1], 0x20
	s_waitcnt vmcnt(0) lgkmcnt(0)
	s_lshl_b32 s2, s73, 3
	s_add_i32 s2, s2, s83
	s_cmpk_gt_i32 s2, 0xff
	s_cbranch_scc1 .LBB0_644

; __device__ __forceinline__ const float* in_sel(const Args& a, int idx) {
;     switch (idx) {
;         case 5: return uni(a.in[5]); case 6: return uni(a.in[6]); case 8: return uni(a.in[8]); case 9: return uni(a.in[9]); case 10: return uni(a.in[10]); case 11: return uni(a.in[11]); case 12: return uni(a.in[12]);
;         case 17: return uni(a.in[17]); case 18: return uni(a.in[18]); case 19: return uni(a.in[19]); case 21: return uni(a.in[21]); default: return uni(a.in[22]);
;     }
.LBB0_734:
	s_mov_b64 s[28:29], -1
	s_mov_b64 s[26:27], 0
	s_cmp_lt_i32 s23, 11
	s_mov_b64 s[18:19], 0
	s_cbranch_scc1 .LBB0_762
	s_cmp_gt_i32 s23, 17
	s_cbranch_scc0 .LBB0_742
	s_cmp_gt_i32 s23, 18
	s_cbranch_scc0 .LBB0_743
	s_cmp_gt_i32 s23, 20
	s_cbranch_scc0 .LBB0_746
	s_cmp_eq_u32 s23, 21
	s_mov_b64 s[18:19], -1
	s_cbranch_scc0 .LBB0_740
	s_load_dwordx2 s[14:15], s[0:1], 0xa8
	s_mov_b64 s[18:19], 0
	s_waitcnt vmcnt(0) lgkmcnt(0)

; __device__ __forceinline__ const float* in_sel(const Args& a, int idx) {
;     switch (idx) {
;         case 5: return uni(a.in[5]); case 6: return uni(a.in[6]); case 8: return uni(a.in[8]); case 9: return uni(a.in[9]); case 10: return uni(a.in[10]); case 11: return uni(a.in[11]); case 12: return uni(a.in[12]);
;         case 17: return uni(a.in[17]); case 18: return uni(a.in[18]); case 19: return uni(a.in[19]); case 21: return uni(a.in[21]); default: return uni(a.in[22]);
;     }
.LBB0_746:
	s_and_b64 vcc, exec, s[28:29]
	s_cbranch_vccz .LBB0_749
	s_cmp_eq_u32 s23, 19
	s_mov_b64 s[18:19], -1
	s_cbranch_scc0 .LBB0_749
	s_load_dwordx2 s[14:15], s[0:1], 0x98
	s_mov_b64 s[18:19], 0
	s_waitcnt vmcnt(0) lgkmcnt(0)

; __device__ __forceinline__ const float* in_sel(const Args& a, int idx) {
;     switch (idx) {
;         case 5: return uni(a.in[5]); case 6: return uni(a.in[6]); case 8: return uni(a.in[8]); case 9: return uni(a.in[9]); case 10: return uni(a.in[10]); case 11: return uni(a.in[11]); case 12: return uni(a.in[12]);
;         case 17: return uni(a.in[17]); case 18: return uni(a.in[18]); case 19: return uni(a.in[19]); case 21: return uni(a.in[21]); default: return uni(a.in[22]);
;     }
.LBB0_750:
	s_load_dwordx2 s[14:15], s[0:1], 0x90
	s_waitcnt vmcnt(0) lgkmcnt(0)

; __device__ __forceinline__ const float* in_sel(const Args& a, int idx) {
;     switch (idx) {
;         case 5: return uni(a.in[5]); case 6: return uni(a.in[6]); case 8: return uni(a.in[8]); case 9: return uni(a.in[9]); case 10: return uni(a.in[10]); case 11: return uni(a.in[11]); case 12: return uni(a.in[12]);
;         case 17: return uni(a.in[17]); case 18: return uni(a.in[18]); case 19: return uni(a.in[19]); case 21: return uni(a.in[21]); default: return uni(a.in[22]);
;     }
.LBB0_752:
	s_cmp_gt_i32 s23, 11
	s_mov_b64 s[28:29], -1
	s_cbranch_scc0 .LBB0_759
	s_cmp_gt_i32 s23, 16
	s_cbranch_scc0 .LBB0_755
	s_load_dwordx2 s[14:15], s[0:1], 0x88
	s_mov_b64 s[28:29], 0
	s_waitcnt vmcnt(0) lgkmcnt(0)
.LBB0_755:
	s_andn2_b64 vcc, exec, s[28:29]
	s_cbranch_vccnz .LBB0_758
	s_cmp_eq_u32 s23, 12
	s_mov_b64 s[18:19], -1
	s_cbranch_scc0 .LBB0_758
	s_load_dwordx2 s[14:15], s[0:1], 0x60
	s_mov_b64 s[18:19], 0
	s_waitcnt vmcnt(0) lgkmcnt(0)

; __device__ __forceinline__ const float* in_sel(const Args& a, int idx) {
;     switch (idx) {
;         case 5: return uni(a.in[5]); case 6: return uni(a.in[6]); case 8: return uni(a.in[8]); case 9: return uni(a.in[9]); case 10: return uni(a.in[10]); case 11: return uni(a.in[11]); case 12: return uni(a.in[12]);
;         case 17: return uni(a.in[17]); case 18: return uni(a.in[18]); case 19: return uni(a.in[19]); case 21: return uni(a.in[21]); default: return uni(a.in[22]);
;     }
.LBB0_759:
	s_and_b64 vcc, exec, s[28:29]
	s_cbranch_vccz .LBB0_761
	s_load_dwordx2 s[14:15], s[0:1], 0x58
	s_waitcnt vmcnt(0) lgkmcnt(0)

; __device__ __forceinline__ const float* in_sel(const Args& a, int idx) {
;     switch (idx) {
;         case 5: return uni(a.in[5]); case 6: return uni(a.in[6]); case 8: return uni(a.in[8]); case 9: return uni(a.in[9]); case 10: return uni(a.in[10]); case 11: return uni(a.in[11]); case 12: return uni(a.in[12]);
;         case 17: return uni(a.in[17]); case 18: return uni(a.in[18]); case 19: return uni(a.in[19]); case 21: return uni(a.in[21]); default: return uni(a.in[22]);
;     }
.LBB0_762:
	s_and_b64 vcc, exec, s[28:29]
	s_cbranch_vccz .LBB0_776
	s_cmp_gt_i32 s23, 7
	s_mov_b64 s[26:27], -1
	s_cbranch_scc0 .LBB0_773
	s_cmp_lt_i32 s23, 9
	s_cbranch_scc1 .LBB0_770
	s_cmp_gt_i32 s23, 9
	s_cbranch_scc0 .LBB0_767
	s_load_dwordx2 s[14:15], s[0:1], 0x50
	s_mov_b64 s[26:27], 0
	s_waitcnt vmcnt(0) lgkmcnt(0)
.LBB0_767:
	s_andn2_b64 vcc, exec, s[26:27]
	s_cbranch_vccnz .LBB0_769
	s_load_dwordx2 s[14:15], s[0:1], 0x48
	s_waitcnt vmcnt(0) lgkmcnt(0)

; __device__ __forceinline__ const float* in_sel(const Args& a, int idx) {
;     switch (idx) {
;         case 5: return uni(a.in[5]); case 6: return uni(a.in[6]); case 8: return uni(a.in[8]); case 9: return uni(a.in[9]); case 10: return uni(a.in[10]); case 11: return uni(a.in[11]); case 12: return uni(a.in[12]);
;         case 17: return uni(a.in[17]); case 18: return uni(a.in[18]); case 19: return uni(a.in[19]); case 21: return uni(a.in[21]); default: return uni(a.in[22]);
;     }
.LBB0_770:
	s_andn2_b64 vcc, exec, s[26:27]
	s_cbranch_vccnz .LBB0_772
	s_load_dwordx2 s[14:15], s[0:1], 0x40
	s_waitcnt vmcnt(0) lgkmcnt(0)

; __device__ __forceinline__ const float* in_sel(const Args& a, int idx) {
;     switch (idx) {
;         case 5: return uni(a.in[5]); case 6: return uni(a.in[6]); case 8: return uni(a.in[8]); case 9: return uni(a.in[9]); case 10: return uni(a.in[10]); case 11: return uni(a.in[11]); case 12: return uni(a.in[12]);
;         case 17: return uni(a.in[17]); case 18: return uni(a.in[18]); case 19: return uni(a.in[19]); case 21: return uni(a.in[21]); default: return uni(a.in[22]);
;     }
.LBB0_777:
	s_load_dwordx2 s[14:15], s[0:1], 0xb0
	s_mov_b64 s[28:29], 0
	s_waitcnt vmcnt(0) lgkmcnt(0)
.LBB0_778:
	s_andn2_b64 vcc, exec, s[28:29]
	s_cbranch_vccnz .LBB0_780
	s_load_dwordx2 s[14:15], s[0:1], 0x30
	s_waitcnt vmcnt(0) lgkmcnt(0)
	s_andn2_b64 vcc, exec, s[26:27]
	s_cbranch_vccz .LBB0_781
	s_branch .LBB0_782

; __device__ __forceinline__ const float* in_sel(const Args& a, int idx) {
;     switch (idx) {
;         case 5: return uni(a.in[5]); case 6: return uni(a.in[6]); case 8: return uni(a.in[8]); case 9: return uni(a.in[9]); case 10: return uni(a.in[10]); case 11: return uni(a.in[11]); case 12: return uni(a.in[12]);
;         case 17: return uni(a.in[17]); case 18: return uni(a.in[18]); case 19: return uni(a.in[19]); case 21: return uni(a.in[21]); default: return uni(a.in[22]);
;     }
; __device__ __forceinline__ void p0_prologue(Frame& F, const Args& A, unsigned char* ws) {
;     ...
;         const float* W = in_sel(A, in_idx) + (size_t)l * K * Ns;
;         const float* gain = gain_idx >= 0 ? in_sel(A, gain_idx) + (size_t)l * K : nullptr;
.LBB0_781:
	s_load_dwordx2 s[14:15], s[0:1], 0x28
	s_waitcnt vmcnt(0) lgkmcnt(0)
.LBB0_782:
	s_ashr_i32 s18, s17, 31
	s_mul_hi_u32 s19, s8, s17
	s_mul_i32 s18, s8, s18
	s_add_i32 s18, s19, s18
	s_mul_i32 s19, s9, s17
	s_add_i32 s27, s18, s19
	s_mul_i32 s26, s8, s17
	s_andn2_b64 vcc, exec, s[6:7]
	s_mov_b64 s[18:19], 0
	s_cbranch_vccnz .LBB0_791
	s_cmp_gt_i32 s21, 10
	s_mov_b64 s[18:19], -1
	s_cbranch_scc0 .LBB0_785
	s_load_dwordx2 s[6:7], s[0:1], 0x58
	s_mov_b64 s[18:19], 0
	s_waitcnt vmcnt(0) lgkmcnt(0)
.LBB0_785:
	s_andn2_b64 vcc, exec, s[18:19]
	s_cbranch_vccnz .LBB0_790
	s_cmp_lg_u32 s21, 9
	s_mov_b64 s[18:19], -1
	s_cbranch_scc0 .LBB0_788
	s_load_dwordx2 s[6:7], s[0:1], 0xb0
	s_mov_b64 s[18:19], 0
	s_waitcnt vmcnt(0) lgkmcnt(0)
.LBB0_788:
	s_andn2_b64 vcc, exec, s[18:19]
	s_cbranch_vccnz .LBB0_790
	s_load_dwordx2 s[6:7], s[0:1], 0x48
	s_waitcnt vmcnt(0) lgkmcnt(0)

; __global__ void __launch_bounds__(NTHR, 2) fwd_megakernel(Args args) {
;     extern __shared__ __attribute__((aligned(16))) unsigned char lds_raw[];
	.amdhsa_kernel _Z14fwd_megakernel4Args
		.amdhsa_group_segment_fixed_size 0
		.amdhsa_private_segment_fixed_size 0
		.amdhsa_kernarg_size 464
		.amdhsa_user_sgpr_count 2
		.amdhsa_user_sgpr_dispatch_ptr 0
		.amdhsa_user_sgpr_queue_ptr 0
		.amdhsa_user_sgpr_kernarg_segment_ptr 1
		.amdhsa_user_sgpr_dispatch_id 0
		.amdhsa_user_sgpr_kernarg_preload_length 0
		.amdhsa_user_sgpr_kernarg_preload_offset 0
		.amdhsa_user_sgpr_private_segment_size 0
		.amdhsa_uses_dynamic_stack 0
		.amdhsa_enable_private_segment 0
		.amdhsa_system_sgpr_workgroup_id_x 1
		.amdhsa_system_sgpr_workgroup_id_y 0
		.amdhsa_system_sgpr_workgroup_id_z 0
		.amdhsa_system_sgpr_workgroup_info 0
		.amdhsa_system_vgpr_workitem_id 2
		.amdhsa_next_free_vgpr 249
		.amdhsa_next_free_sgpr 102
		.amdhsa_accum_offset 252
		.amdhsa_reserve_vcc 1
		.amdhsa_float_round_mode_32 0
		.amdhsa_float_round_mode_16_64 0
		.amdhsa_float_denorm_mode_32 3
		.amdhsa_float_denorm_mode_16_64 3
		.amdhsa_dx10_clamp 1
		.amdhsa_ieee_mode 1
		.amdhsa_fp16_overflow 0
		.amdhsa_tg_split 0
		.amdhsa_exception_fp_ieee_invalid_op 0
		.amdhsa_exception_fp_denorm_src 0
		.amdhsa_exception_fp_ieee_div_zero 0
		.amdhsa_exception_fp_ieee_overflow 0
		.amdhsa_exception_fp_ieee_underflow 0
		.amdhsa_exception_fp_ieee_inexact 0
		.amdhsa_exception_int_div_zero 0
	.end_amdhsa_kernel

; __global__ void __launch_bounds__(NTHR, 2) fwd_megakernel(Args args) {
amdhsa.kernels:
  - .agpr_count:     0
    .args:
      - .offset:         0
        .size:           208
        .value_kind:     by_value
      - .offset:         208
        .size:           4
        .value_kind:     hidden_block_count_x
      - .offset:         212
        .size:           4
        .value_kind:     hidden_block_count_y
      - .offset:         216
        .size:           4
        .value_kind:     hidden_block_count_z
      - .offset:         220
        .size:           2
        .value_kind:     hidden_group_size_x
      - .offset:         222
        .size:           2
        .value_kind:     hidden_group_size_y
      - .offset:         224
        .size:           2
        .value_kind:     hidden_group_size_z
      - .offset:         226
        .size:           2
        .value_kind:     hidden_remainder_x
      - .offset:         228
        .size:           2
        .value_kind:     hidden_remainder_y
      - .offset:         230
        .size:           2
        .value_kind:     hidden_remainder_z
      - .offset:         248
        .size:           8
        .value_kind:     hidden_global_offset_x
      - .offset:         256
        .size:           8
        .value_kind:     hidden_global_offset_y
      - .offset:         264
        .size:           8
        .value_kind:     hidden_global_offset_z
      - .offset:         272
        .size:           2
        .value_kind:     hidden_grid_dims
      - .offset:         296
        .size:           8
        .value_kind:     hidden_multigrid_sync_arg
      - .offset:         328
        .size:           4
        .value_kind:     hidden_dynamic_lds_size
    .group_segment_fixed_size: 0
    .kernarg_segment_align: 8
    .kernarg_segment_size: 464
    .language:       OpenCL C
    .language_version:
      - 2
      - 0
    .max_flat_workgroup_size: 512
    .name:           _Z14fwd_megakernel4Args
    .private_segment_fixed_size: 0
    .sgpr_count:     108
    .sgpr_spill_count: 49
    .symbol:         _Z14fwd_megakernel4Args.kd
    .uniform_work_group_size: 1
    .uses_dynamic_stack: false
    .vgpr_count:     249
    .vgpr_spill_count: 0
    .wavefront_size: 64
